# P0 weight-copy items rebalanced: waves with an adaLN GEMV item copy 4 tiles, the others 6 (was 4-5 vs 5)
# speedup vs baseline: 1.0022x; 1.0022x over previous
; __device__ __forceinline__ float silu_f(float x) { return x * __builtin_amdgcn_rcpf(1.f + __expf(-x)); }
; #define TP_BEGIN(k) do { if (TIME_PHASE == (k)) tp_a = __builtin_amdgcn_s_memrealtime(); } while (0)
; __global__ void __launch_bounds__(NTHR, 2) fwd_kernel(Args args) {
;     ...
;     if (IN(PH_PRO)) { TP_BEGIN(PH_PRO);
;       for (int rep_ = 0; rep_ < REPS(PH_PRO); ++rep_) {
;         if (gw < I_GV) {
;             const int r = gw, s = r / (NMOD / 64), col = (r % (NMOD / 64)) * 64 + lane;
;             float a0 = 0.f, a1 = 0.f, a2 = 0.f;
;             for (int kb = 0; kb < 4; ++kb) {
;                 const int kbase = s * 256 + kb * 64;
;                 const float c0 = silu_f(args.in[IN_C][kbase + lane]), c1 = silu_f(args.in[IN_C][D + kbase + lane]), c2 = silu_f(args.in[IN_CCTX][kbase + lane]);
;                 const float* wp = args.in[IN_WMOD] + (size_t)kbase * NMOD + col;
;                 float wv[64];
; #pragma unroll
;                 for (int kk = 0; kk < 64; ++kk) wv[kk] = __builtin_nontemporal_load(wp + (size_t)kk * NMOD);
.LBB0_5:
	s_or_b64 exec, exec, s[4:5]
	s_lshl_b32 s3, s2, 3
	s_add_i32 s20, s88, s3
	s_lshl_b32 s22, s90, 3
	s_add_u32 s54, s18, 0x100000
	s_addc_u32 s55, s19, 0
	s_add_u32 s82, s18, 0x104000
	s_addc_u32 s83, s19, 0
	s_add_u32 s40, s18, 0x108000
	s_addc_u32 s41, s19, 0
	s_load_dwordx2 s[94:95], s[0:1], 0xa0
	s_add_u32 s10, s18, 0x10000
	s_addc_u32 s11, s19, 0
	s_add_u32 s50, s18, 0x4400000
	s_addc_u32 s51, s19, 0
	s_waitcnt lgkmcnt(0)
	s_cmp_lt_i32 s94, 1
	s_cselect_b64 s[4:5], -1, 0
	s_cmp_gt_i32 s95, 0
	s_cselect_b64 s[6:7], -1, 0
	s_and_b64 s[4:5], s[4:5], s[6:7]
	v_writelane_b32 v255, s84, 2
	v_and_b32_e32 v216, 63, v0
	s_andn2_b64 vcc, exec, s[4:5]
	v_lshl_or_b32 v162, s2, 9, v0
	v_writelane_b32 v255, s85, 3
	s_cbranch_vccnz .LBB0_173
	s_cmpk_gt_i32 s20, 0x5ff
	s_movk_i32 s6, 0x1800
	s_cbranch_scc1 .LBB0_10
	s_mul_hi_i32 s4, s20, 0x2aaaaaab
	s_lshr_b32 s5, s4, 31
	s_ashr_i32 s12, s4, 5
	s_add_i32 s12, s12, s5
	s_load_dwordx2 s[8:9], s[0:1], 0x8
	s_load_dwordx4 s[4:7], s[0:1], 0x18
	v_writelane_b32 v255, s82, 4
	s_lshl_b32 s13, s12, 8
	s_mul_i32 s14, s12, 0xc00000
	v_lshl_or_b32 v1, s20, 6, v216
	s_mul_i32 s15, s12, 0x3000
	v_writelane_b32 v255, s83, 5
	v_or_b32_e32 v2, s13, v216
	s_mul_hi_i32 s13, s13, 0xc000
	v_subrev_u32_e32 v4, s15, v1
	s_waitcnt lgkmcnt(0)
	s_add_u32 s6, s6, s14
	v_writelane_b32 v255, s54, 6
	v_ashrrev_i32_e32 v5, 31, v4
	s_addc_u32 s7, s7, s13
	v_mov_b32_e32 v1, 0
	v_writelane_b32 v255, s55, 7
	s_mov_b32 s25, s88
	v_lshl_add_u64 v[4:5], v[4:5], 2, s[6:7]
	s_mov_b64 s[6:7], 0
	s_mov_b32 s13, 0x114000
	s_mov_b32 s21, 0x120000
	s_mov_b32 s23, 0x12c000
	s_mov_b32 s30, 0x138000
	s_mov_b32 s31, 0x144000
	s_mov_b32 s34, 0x150000
	s_mov_b32 s35, 0x15c000
	s_mov_b32 s36, 0x168000
	s_mov_b32 s37, 0x174000
	s_mov_b32 s38, 0x180000
	s_mov_b32 s39, 0x18c000
	s_mov_b32 s42, 0x198000
	s_mov_b32 s43, 0x1a4000
	s_mov_b32 s44, 0x1b0000
	s_mov_b32 s45, 0x1bc000
	s_mov_b32 s46, 0x1c8000
	s_mov_b32 s47, 0x1d4000
	s_mov_b32 s48, 0x1e0000
	s_mov_b32 s49, 0x1ec000
	s_mov_b32 s56, 0x1f8000
	s_mov_b32 s57, 0x204000
	s_mov_b32 s58, 0x210000
	s_mov_b32 s59, 0x21c000
	s_mov_b32 s60, 0x228000
	s_mov_b32 s61, 0x234000
	s_mov_b32 s62, 0x240000
	s_mov_b32 s63, 0x24c000
	s_mov_b32 s64, 0x258000
	s_mov_b32 s65, 0x264000
	s_mov_b32 s66, 0x270000
	s_mov_b32 s67, 0x27c000
	s_mov_b32 s68, 0x288000
	s_mov_b32 s69, 0x294000
	s_mov_b32 s70, 0x2a0000
	s_mov_b32 s71, 0x2ac000
	s_mov_b32 s72, 0x2b8000
	s_mov_b32 s73, 0x2c4000
	s_mov_b32 s74, 0x2d0000
	s_mov_b32 s75, 0x2dc000
	s_mov_b32 s76, 0x2e8000
	s_mov_b32 s77, 0x2f4000
	v_mov_b32_e32 v6, 0
	v_mov_b32_e32 v7, v1
.LBB0_8:
	v_ashrrev_i32_e32 v3, 31, v2
	v_lshlrev_b64 v[8:9], 2, v[2:3]
	v_lshl_add_u64 v[10:11], s[8:9], 0, v[8:9]
	global_load_dword v3, v[10:11], off
	v_lshl_add_u64 v[8:9], s[4:5], 0, v[8:9]
	global_load_dword v9, v[8:9], off
	v_lshl_add_u64 v[82:83], v[4:5], 0, s[6:7]
	s_mov_b32 s14, 0xc000
	s_add_u32 s6, s6, 0x300000
	s_addc_u32 s7, s7, 0
	s_cmp_eq_u32 s6, 0xc00000
	s_waitcnt vmcnt(1)
	v_mul_f32_e32 v10, 0xbfb8aa3b, v3
	v_exp_f32_e32 v10, v10
	s_waitcnt vmcnt(0)
	v_mul_f32_e32 v8, 0xbfb8aa3b, v9
	v_exp_f32_e32 v8, v8
	v_add_f32_e32 v10, 1.0, v10
	v_rcp_f32_e32 v15, v10
	v_add_u32_e32 v10, 0x800, v2
	v_ashrrev_i32_e32 v11, 31, v10
	v_lshl_add_u64 v[10:11], v[10:11], 2, s[8:9]
	global_load_dword v19, v[10:11], off
	v_add_f32_e32 v8, 1.0, v8
	v_rcp_f32_e32 v27, v8
	global_load_dword v8, v[82:83], off nt
	v_mul_f32_e32 v3, v3, v15
	v_add_u32_e32 v2, 64, v2
	v_readlane_b32 s26, v3, 1
	v_readlane_b32 s28, v3, 2
	v_readlane_b32 s52, v3, 3
	v_readlane_b32 s54, v3, 4
	v_readlane_b32 s78, v3, 5
	v_readlane_b32 s80, v3, 6
	v_readlane_b32 s82, v3, 7
	v_readlane_b32 s84, v3, 8
	v_readlane_b32 s86, v3, 18
	v_readlane_b32 s88, v3, 19
	v_readlane_b32 s92, v3, 52
	s_waitcnt vmcnt(1)
	v_mul_f32_e32 v10, 0xbfb8aa3b, v19
	v_exp_f32_e32 v10, v10
	s_nop 0
	v_add_f32_e32 v10, 1.0, v10
	v_rcp_f32_e32 v23, v10
	v_add_co_u32_e32 v10, vcc, s14, v82
	s_mov_b32 s14, 0x18000
	s_nop 0
	v_addc_co_u32_e32 v11, vcc, 0, v83, vcc
	v_add_co_u32_e32 v12, vcc, s14, v82
	s_mov_b32 s14, 0x24000
	s_nop 0
	v_addc_co_u32_e32 v13, vcc, 0, v83, vcc
	global_load_dword v10, v[10:11], off nt
	s_nop 0
	global_load_dword v14, v[12:13], off nt
	v_add_co_u32_e32 v12, vcc, s14, v82
	s_mov_b32 s14, 0x30000
	s_nop 0
	v_addc_co_u32_e32 v13, vcc, 0, v83, vcc
	global_load_dword v18, v[12:13], off nt
	v_add_co_u32_e32 v12, vcc, s14, v82
	s_mov_b32 s14, 0x3c000
	s_nop 0
	v_addc_co_u32_e32 v13, vcc, 0, v83, vcc
	global_load_dword v22, v[12:13], off nt
	v_add_co_u32_e32 v12, vcc, s14, v82
	s_mov_b32 s14, 0x48000
	s_nop 0
	v_addc_co_u32_e32 v13, vcc, 0, v83, vcc
	global_load_dword v26, v[12:13], off nt
	v_add_co_u32_e32 v12, vcc, s14, v82
	s_mov_b32 s14, 0x54000
	s_nop 0
	v_addc_co_u32_e32 v13, vcc, 0, v83, vcc
	global_load_dword v32, v[12:13], off nt
	v_add_co_u32_e32 v12, vcc, s14, v82
	s_mov_b32 s14, 0x60000
	s_nop 0
	v_addc_co_u32_e32 v13, vcc, 0, v83, vcc
	global_load_dword v38, v[12:13], off nt
	v_add_co_u32_e32 v12, vcc, s14, v82
	s_mov_b32 s14, 0x6c000
	s_nop 0
	v_addc_co_u32_e32 v13, vcc, 0, v83, vcc
	global_load_dword v40, v[12:13], off nt
	v_add_co_u32_e32 v12, vcc, s14, v82
	s_mov_b32 s14, 0x78000
	s_nop 0
	v_addc_co_u32_e32 v13, vcc, 0, v83, vcc
	v_add_co_u32_e32 v16, vcc, s14, v82
	s_mov_b32 s14, 0x84000
	s_nop 0
	v_addc_co_u32_e32 v17, vcc, 0, v83, vcc
	v_add_co_u32_e32 v20, vcc, s14, v82
	s_mov_b32 s14, 0x90000
	s_nop 0
	v_addc_co_u32_e32 v21, vcc, 0, v83, vcc
	v_add_co_u32_e32 v24, vcc, s14, v82
	s_mov_b32 s14, 0x9c000
	s_nop 0
	v_addc_co_u32_e32 v25, vcc, 0, v83, vcc
	v_add_co_u32_e32 v28, vcc, s14, v82
	s_mov_b32 s14, 0xa8000
; __global__ void __launch_bounds__(NTHR, 2) fwd_kernel(Args args) {
;     ...
;                 for (int kk = 0; kk < 64; ++kk) wv[kk] = __builtin_nontemporal_load(wp + (size_t)kk * NMOD);
; #pragma unroll
;                 for (int kk = 0; kk < 64; ++kk) {
;                     a0 += wv[kk] * __builtin_bit_cast(float, __builtin_amdgcn_readlane(__builtin_bit_cast(int, c0), kk));
;                     a1 += wv[kk] * __builtin_bit_cast(float, __builtin_amdgcn_readlane(__builtin_bit_cast(int, c1), kk));
;                     a2 += wv[kk] * __builtin_bit_cast(float, __builtin_amdgcn_readlane(__builtin_bit_cast(int, c2), kk));
;                 }
	s_nop 0
	v_addc_co_u32_e32 v29, vcc, 0, v83, vcc
	global_load_dword v12, v[12:13], off nt
	v_mul_f32_e32 v11, v19, v23
	global_load_dword v16, v[16:17], off nt
	v_readlane_b32 s15, v11, 0
	global_load_dword v20, v[20:21], off nt
	v_readlane_b32 s27, v11, 1
	global_load_dword v24, v[24:25], off nt
	v_readlane_b32 s29, v11, 2
	global_load_dword v30, v[28:29], off nt
	v_add_co_u32_e32 v28, vcc, s14, v82
	s_mov_b32 s14, 0xb4000
	s_nop 0
	v_addc_co_u32_e32 v29, vcc, 0, v83, vcc
	global_load_dword v36, v[28:29], off nt
	v_add_co_u32_e32 v28, vcc, s14, v82
	s_mov_b32 s14, 0xc0000
	s_nop 0
	v_addc_co_u32_e32 v29, vcc, 0, v83, vcc
	global_load_dword v42, v[28:29], off nt
	v_add_co_u32_e32 v28, vcc, s14, v82
	s_mov_b32 s14, 0xcc000
	s_nop 0
	v_addc_co_u32_e32 v29, vcc, 0, v83, vcc
	global_load_dword v46, v[28:29], off nt
	v_add_co_u32_e32 v28, vcc, s14, v82
	s_mov_b32 s14, 0xd8000
	s_nop 0
	v_addc_co_u32_e32 v29, vcc, 0, v83, vcc
	global_load_dword v52, v[28:29], off nt
	v_add_co_u32_e32 v28, vcc, s14, v82
	s_mov_b32 s14, 0xe4000
	s_nop 0
	v_addc_co_u32_e32 v29, vcc, 0, v83, vcc
	global_load_dword v56, v[28:29], off nt
	v_add_co_u32_e32 v28, vcc, s14, v82
	s_mov_b32 s14, 0xf0000
	s_nop 0
	v_addc_co_u32_e32 v29, vcc, 0, v83, vcc
	global_load_dword v64, v[28:29], off nt
	v_add_co_u32_e32 v28, vcc, s14, v82
	s_mov_b32 s14, 0xfc000
	s_nop 0
	v_addc_co_u32_e32 v29, vcc, 0, v83, vcc
	v_add_co_u32_e32 v34, vcc, s14, v82
	s_mov_b32 s14, 0x108000
	s_nop 0
	v_addc_co_u32_e32 v35, vcc, 0, v83, vcc
	v_add_co_u32_e32 v44, vcc, s14, v82
	global_load_dword v28, v[28:29], off nt
	s_nop 0
	v_addc_co_u32_e32 v45, vcc, 0, v83, vcc
	global_load_dword v34, v[34:35], off nt
	v_mul_f32_e32 v13, v9, v27
	global_load_dword v98, v[44:45], off nt
	v_add_co_u32_e32 v44, vcc, s13, v82
	v_readlane_b32 s14, v3, 0
	s_nop 0
	v_addc_co_u32_e32 v45, vcc, 0, v83, vcc
	global_load_dword v102, v[44:45], off nt
	v_add_co_u32_e32 v44, vcc, s21, v82
	v_readlane_b32 s24, v13, 0
	s_nop 0
	v_addc_co_u32_e32 v45, vcc, 0, v83, vcc
	global_load_dword v106, v[44:45], off nt
	v_add_co_u32_e32 v44, vcc, s23, v82
	s_waitcnt vmcnt(24)
	v_fmac_f32_e32 v1, s24, v8
	v_addc_co_u32_e32 v45, vcc, 0, v83, vcc
	global_load_dword v110, v[44:45], off nt
	v_add_co_u32_e32 v44, vcc, s30, v82
	v_readlane_b32 s24, v13, 1
	s_nop 0
	v_addc_co_u32_e32 v45, vcc, 0, v83, vcc
	global_load_dword v116, v[44:45], off nt
	v_add_co_u32_e32 v44, vcc, s31, v82
	v_pk_fma_f32 v[6:7], v[8:9], s[14:15], v[6:7] op_sel_hi:[0,1,1]
	s_nop 0
	v_addc_co_u32_e32 v45, vcc, 0, v83, vcc
	global_load_dword v118, v[44:45], off nt
	v_add_co_u32_e32 v44, vcc, s34, v82
	s_waitcnt vmcnt(26)
	v_fmac_f32_e32 v1, s24, v10
	v_addc_co_u32_e32 v45, vcc, 0, v83, vcc
	global_load_dword v120, v[44:45], off nt
	v_add_co_u32_e32 v44, vcc, s35, v82
	v_readlane_b32 s24, v13, 2
	s_nop 0
	v_addc_co_u32_e32 v45, vcc, 0, v83, vcc
	global_load_dword v122, v[44:45], off nt
	v_add_co_u32_e32 v44, vcc, s36, v82
	v_pk_fma_f32 v[6:7], v[10:11], s[26:27], v[6:7] op_sel_hi:[0,1,1]
	s_nop 0
	v_addc_co_u32_e32 v45, vcc, 0, v83, vcc
	global_load_dword v124, v[44:45], off nt
	v_add_co_u32_e32 v44, vcc, s37, v82
	s_waitcnt vmcnt(28)
	v_fmac_f32_e32 v1, s24, v14
	v_addc_co_u32_e32 v45, vcc, 0, v83, vcc
	global_load_dword v68, v[44:45], off nt
	v_add_co_u32_e32 v44, vcc, s38, v82
	v_readlane_b32 s53, v11, 3
	s_nop 0
	v_addc_co_u32_e32 v45, vcc, 0, v83, vcc
	global_load_dword v74, v[44:45], off nt
	v_add_co_u32_e32 v44, vcc, s39, v82
	v_readlane_b32 s24, v13, 3
	s_nop 0
	v_addc_co_u32_e32 v45, vcc, 0, v83, vcc
	global_load_dword v78, v[44:45], off nt
	v_add_co_u32_e32 v44, vcc, s42, v82
	v_pk_fma_f32 v[6:7], v[14:15], s[28:29], v[6:7] op_sel_hi:[0,1,1]
	s_nop 0
	v_addc_co_u32_e32 v45, vcc, 0, v83, vcc
	global_load_dword v84, v[44:45], off nt
	v_add_co_u32_e32 v44, vcc, s43, v82
	s_waitcnt vmcnt(31)
	v_fmac_f32_e32 v1, s24, v18
	v_addc_co_u32_e32 v45, vcc, 0, v83, vcc
	global_load_dword v90, v[44:45], off nt
	v_add_co_u32_e32 v44, vcc, s44, v82
	v_readlane_b32 s55, v11, 4
	s_nop 0
	v_addc_co_u32_e32 v45, vcc, 0, v83, vcc
	global_load_dword v94, v[44:45], off nt
	v_add_co_u32_e32 v44, vcc, s45, v82
	v_readlane_b32 s24, v13, 4
	s_nop 0
	v_addc_co_u32_e32 v45, vcc, 0, v83, vcc
	global_load_dword v100, v[44:45], off nt
	v_add_co_u32_e32 v44, vcc, s46, v82
	v_pk_fma_f32 v[6:7], v[18:19], s[52:53], v[6:7] op_sel_hi:[0,1,1]
	s_nop 0
	v_addc_co_u32_e32 v45, vcc, 0, v83, vcc
	global_load_dword v104, v[44:45], off nt
	v_add_co_u32_e32 v44, vcc, s47, v82
	s_waitcnt vmcnt(34)
	v_fmac_f32_e32 v1, s24, v22
	v_addc_co_u32_e32 v45, vcc, 0, v83, vcc
	global_load_dword v108, v[44:45], off nt
	v_add_co_u32_e32 v44, vcc, s48, v82
	v_readlane_b32 s79, v11, 5
	s_nop 0
	v_addc_co_u32_e32 v45, vcc, 0, v83, vcc
	global_load_dword v112, v[44:45], off nt
	v_add_co_u32_e32 v44, vcc, s49, v82
	v_readlane_b32 s24, v13, 5
	s_nop 0
	v_addc_co_u32_e32 v45, vcc, 0, v83, vcc
	global_load_dword v114, v[44:45], off nt
	v_add_co_u32_e32 v44, vcc, s56, v82
	v_pk_fma_f32 v[6:7], v[22:23], s[54:55], v[6:7] op_sel_hi:[0,1,1]
	s_nop 0
	v_addc_co_u32_e32 v45, vcc, 0, v83, vcc
	global_load_dword v54, v[44:45], off nt
	v_add_co_u32_e32 v44, vcc, s57, v82
	s_waitcnt vmcnt(37)
	v_fmac_f32_e32 v1, s24, v26
	v_addc_co_u32_e32 v45, vcc, 0, v83, vcc
	global_load_dword v58, v[44:45], off nt
	v_add_co_u32_e32 v44, vcc, s58, v82
	v_readlane_b32 s81, v11, 6
	s_nop 0
	v_addc_co_u32_e32 v45, vcc, 0, v83, vcc
	global_load_dword v62, v[44:45], off nt
	v_add_co_u32_e32 v44, vcc, s59, v82
	v_readlane_b32 s24, v13, 6
	s_nop 0
	v_addc_co_u32_e32 v45, vcc, 0, v83, vcc
	global_load_dword v66, v[44:45], off nt
	v_add_co_u32_e32 v44, vcc, s60, v82
	v_pk_fma_f32 v[6:7], v[26:27], s[78:79], v[6:7] op_sel_hi:[0,1,1]
	s_nop 0
	v_addc_co_u32_e32 v45, vcc, 0, v83, vcc
	global_load_dword v70, v[44:45], off nt
	v_add_co_u32_e32 v44, vcc, s61, v82
	s_waitcnt vmcnt(40)
; __global__ void __launch_bounds__(NTHR, 2) fwd_kernel(Args args) {
;     ...
;                 for (int kk = 0; kk < 64; ++kk) wv[kk] = __builtin_nontemporal_load(wp + (size_t)kk * NMOD);
; #pragma unroll
;                 for (int kk = 0; kk < 64; ++kk) {
;                     a0 += wv[kk] * __builtin_bit_cast(float, __builtin_amdgcn_readlane(__builtin_bit_cast(int, c0), kk));
;                     a1 += wv[kk] * __builtin_bit_cast(float, __builtin_amdgcn_readlane(__builtin_bit_cast(int, c1), kk));
;                     a2 += wv[kk] * __builtin_bit_cast(float, __builtin_amdgcn_readlane(__builtin_bit_cast(int, c2), kk));
;                 }
	v_fmac_f32_e32 v1, s24, v32
	v_addc_co_u32_e32 v45, vcc, 0, v83, vcc
	global_load_dword v76, v[44:45], off nt
	v_add_co_u32_e32 v44, vcc, s62, v82
	v_readlane_b32 s83, v11, 7
	s_nop 0
	v_addc_co_u32_e32 v45, vcc, 0, v83, vcc
	global_load_dword v80, v[44:45], off nt
	v_add_co_u32_e32 v44, vcc, s63, v82
	v_readlane_b32 s24, v13, 7
	s_nop 0
	v_addc_co_u32_e32 v45, vcc, 0, v83, vcc
	global_load_dword v86, v[44:45], off nt
	v_add_co_u32_e32 v44, vcc, s64, v82
	v_pk_fma_f32 v[6:7], v[32:33], s[80:81], v[6:7] op_sel_hi:[0,1,1]
	s_nop 0
	v_addc_co_u32_e32 v45, vcc, 0, v83, vcc
	global_load_dword v92, v[44:45], off nt
	v_add_co_u32_e32 v44, vcc, s65, v82
	s_waitcnt vmcnt(43)
	v_fmac_f32_e32 v1, s24, v38
	v_addc_co_u32_e32 v45, vcc, 0, v83, vcc
	global_load_dword v88, v[44:45], off nt
	v_add_co_u32_e32 v44, vcc, s66, v82
	v_readlane_b32 s85, v11, 8
	s_nop 0
	v_addc_co_u32_e32 v45, vcc, 0, v83, vcc
	global_load_dword v96, v[44:45], off nt
	v_add_co_u32_e32 v44, vcc, s67, v82
	v_pk_fma_f32 v[6:7], v[38:39], s[82:83], v[6:7] op_sel_hi:[0,1,1]
	s_nop 0
	v_addc_co_u32_e32 v45, vcc, 0, v83, vcc
	v_add_co_u32_e32 v48, vcc, s68, v82
	global_load_dword v44, v[44:45], off nt
	s_nop 0
	v_addc_co_u32_e32 v49, vcc, 0, v83, vcc
	global_load_dword v45, v[48:49], off nt
	v_add_co_u32_e32 v48, vcc, s69, v82
	v_readlane_b32 s14, v13, 8
	s_nop 0
	v_addc_co_u32_e32 v49, vcc, 0, v83, vcc
	v_add_co_u32_e32 v50, vcc, s70, v82
	global_load_dword v48, v[48:49], off nt
	s_nop 0
	v_addc_co_u32_e32 v51, vcc, 0, v83, vcc
	global_load_dword v49, v[50:51], off nt
	v_add_co_u32_e32 v50, vcc, s71, v82
	s_waitcnt vmcnt(48)
	v_pk_fma_f32 v[6:7], v[40:41], s[84:85], v[6:7] op_sel_hi:[0,1,1]
	v_addc_co_u32_e32 v51, vcc, 0, v83, vcc
	v_add_co_u32_e32 v60, vcc, s72, v82
	global_load_dword v50, v[50:51], off nt
	s_nop 0
	v_addc_co_u32_e32 v61, vcc, 0, v83, vcc
	global_load_dword v51, v[60:61], off nt
	v_add_co_u32_e32 v60, vcc, s73, v82
	v_fmac_f32_e32 v1, s14, v40
	s_nop 0
	v_addc_co_u32_e32 v61, vcc, 0, v83, vcc
	v_add_co_u32_e32 v72, vcc, s74, v82
	global_load_dword v60, v[60:61], off nt
	s_nop 0
	v_addc_co_u32_e32 v73, vcc, 0, v83, vcc
	global_load_dword v61, v[72:73], off nt
	v_add_co_u32_e32 v72, vcc, s75, v82
	v_readlane_b32 s14, v3, 9
	s_nop 0
	v_addc_co_u32_e32 v73, vcc, 0, v83, vcc
	v_add_co_u32_e32 v126, vcc, s76, v82
	global_load_dword v72, v[72:73], off nt
	s_nop 0
	v_addc_co_u32_e32 v127, vcc, 0, v83, vcc
	v_add_co_u32_e32 v82, vcc, s77, v82
	v_readlane_b32 s15, v11, 9
	s_nop 0
	v_addc_co_u32_e32 v83, vcc, 0, v83, vcc
	global_load_dword v82, v[82:83], off nt
	v_readlane_b32 s24, v13, 9
	global_load_dword v73, v[126:127], off nt
	v_readlane_b32 s26, v3, 10
	s_waitcnt vmcnt(54)
	v_fmac_f32_e32 v1, s24, v12
	v_readlane_b32 s27, v11, 10
	v_readlane_b32 s24, v13, 10
	v_pk_fma_f32 v[6:7], v[12:13], s[14:15], v[6:7] op_sel_hi:[0,1,1]
	v_readlane_b32 s28, v3, 11
	s_waitcnt vmcnt(53)
	v_fmac_f32_e32 v1, s24, v16
	v_readlane_b32 s29, v11, 11
	v_readlane_b32 s24, v13, 11
	v_pk_fma_f32 v[6:7], v[16:17], s[26:27], v[6:7] op_sel_hi:[0,1,1]
	v_readlane_b32 s52, v3, 12
	s_waitcnt vmcnt(52)
	v_fmac_f32_e32 v1, s24, v20
	v_readlane_b32 s53, v11, 12
	v_readlane_b32 s24, v13, 12
	v_pk_fma_f32 v[6:7], v[20:21], s[28:29], v[6:7] op_sel_hi:[0,1,1]
	v_readlane_b32 s54, v3, 13
	s_waitcnt vmcnt(51)
	v_fmac_f32_e32 v1, s24, v24
	v_readlane_b32 s55, v11, 13
	v_readlane_b32 s24, v13, 13
	v_pk_fma_f32 v[6:7], v[24:25], s[52:53], v[6:7] op_sel_hi:[0,1,1]
	v_readlane_b32 s78, v3, 14
	s_waitcnt vmcnt(50)
	v_fmac_f32_e32 v1, s24, v30
	v_readlane_b32 s79, v11, 14
	v_readlane_b32 s24, v13, 14
	v_pk_fma_f32 v[6:7], v[30:31], s[54:55], v[6:7] op_sel_hi:[0,1,1]
	v_readlane_b32 s80, v3, 15
	s_waitcnt vmcnt(49)
	v_fmac_f32_e32 v1, s24, v36
	v_readlane_b32 s81, v11, 15
	v_readlane_b32 s24, v13, 15
	v_pk_fma_f32 v[6:7], v[36:37], s[78:79], v[6:7] op_sel_hi:[0,1,1]
	v_readlane_b32 s82, v3, 16
	s_waitcnt vmcnt(48)
	v_fmac_f32_e32 v1, s24, v42
	v_readlane_b32 s83, v11, 16
	v_readlane_b32 s24, v13, 16
	v_pk_fma_f32 v[6:7], v[42:43], s[80:81], v[6:7] op_sel_hi:[0,1,1]
	v_readlane_b32 s84, v3, 17
	s_waitcnt vmcnt(47)
	v_fmac_f32_e32 v1, s24, v46
	v_readlane_b32 s85, v11, 17
	v_readlane_b32 s24, v13, 17
	v_pk_fma_f32 v[6:7], v[46:47], s[82:83], v[6:7] op_sel_hi:[0,1,1]
	v_readlane_b32 s87, v11, 18
	s_waitcnt vmcnt(46)
	v_fmac_f32_e32 v1, s24, v52
	v_readlane_b32 s24, v13, 18
	v_pk_fma_f32 v[6:7], v[52:53], s[84:85], v[6:7] op_sel_hi:[0,1,1]
	v_readlane_b32 s89, v11, 19
	s_waitcnt vmcnt(45)
	v_fmac_f32_e32 v1, s24, v56
	v_pk_fma_f32 v[6:7], v[56:57], s[86:87], v[6:7] op_sel_hi:[0,1,1]
	v_readlane_b32 s14, v13, 19
	s_waitcnt vmcnt(44)
	v_pk_fma_f32 v[6:7], v[64:65], s[88:89], v[6:7] op_sel_hi:[0,1,1]
	v_readlane_b32 s15, v11, 20
	v_fmac_f32_e32 v1, s14, v64
	v_readlane_b32 s14, v3, 20
	v_readlane_b32 s24, v13, 20
	v_readlane_b32 s26, v3, 21
	v_readlane_b32 s27, v11, 21
	s_waitcnt vmcnt(43)
	v_fmac_f32_e32 v1, s24, v28
	v_readlane_b32 s24, v13, 21
	v_pk_fma_f32 v[6:7], v[28:29], s[14:15], v[6:7] op_sel_hi:[0,1,1]
	v_readlane_b32 s28, v3, 22
	s_waitcnt vmcnt(42)
	v_fmac_f32_e32 v1, s24, v34
	v_readlane_b32 s29, v11, 22
	v_readlane_b32 s24, v13, 22
	v_pk_fma_f32 v[6:7], v[34:35], s[26:27], v[6:7] op_sel_hi:[0,1,1]
	v_readlane_b32 s52, v3, 23
	s_waitcnt vmcnt(41)
	v_fmac_f32_e32 v1, s24, v98
	v_readlane_b32 s53, v11, 23
	v_readlane_b32 s24, v13, 23
	v_pk_fma_f32 v[6:7], v[98:99], s[28:29], v[6:7] op_sel_hi:[0,1,1]
	v_readlane_b32 s54, v3, 24
	s_waitcnt vmcnt(40)
	v_fmac_f32_e32 v1, s24, v102
	v_readlane_b32 s55, v11, 24
	v_readlane_b32 s24, v13, 24
	v_pk_fma_f32 v[6:7], v[102:103], s[52:53], v[6:7] op_sel_hi:[0,1,1]
	v_readlane_b32 s78, v3, 25
	s_waitcnt vmcnt(39)
; __global__ void __launch_bounds__(NTHR, 2) fwd_kernel(Args args) {
;     ...
;                 for (int kk = 0; kk < 64; ++kk) wv[kk] = __builtin_nontemporal_load(wp + (size_t)kk * NMOD);
; #pragma unroll
;                 for (int kk = 0; kk < 64; ++kk) {
;                     a0 += wv[kk] * __builtin_bit_cast(float, __builtin_amdgcn_readlane(__builtin_bit_cast(int, c0), kk));
;                     a1 += wv[kk] * __builtin_bit_cast(float, __builtin_amdgcn_readlane(__builtin_bit_cast(int, c1), kk));
;                     a2 += wv[kk] * __builtin_bit_cast(float, __builtin_amdgcn_readlane(__builtin_bit_cast(int, c2), kk));
;                 }
	v_fmac_f32_e32 v1, s24, v106
	v_readlane_b32 s79, v11, 25
	v_readlane_b32 s24, v13, 25
	v_pk_fma_f32 v[6:7], v[106:107], s[54:55], v[6:7] op_sel_hi:[0,1,1]
	v_readlane_b32 s80, v3, 26
	s_waitcnt vmcnt(38)
	v_fmac_f32_e32 v1, s24, v110
	v_readlane_b32 s81, v11, 26
	v_readlane_b32 s24, v13, 26
	v_pk_fma_f32 v[6:7], v[110:111], s[78:79], v[6:7] op_sel_hi:[0,1,1]
	v_readlane_b32 s82, v3, 27
	s_waitcnt vmcnt(37)
	v_fmac_f32_e32 v1, s24, v116
	v_readlane_b32 s83, v11, 27
	v_readlane_b32 s24, v13, 27
	v_pk_fma_f32 v[6:7], v[116:117], s[80:81], v[6:7] op_sel_hi:[0,1,1]
	v_readlane_b32 s84, v3, 28
	s_waitcnt vmcnt(36)
	v_fmac_f32_e32 v1, s24, v118
	v_readlane_b32 s85, v11, 28
	v_readlane_b32 s24, v13, 28
	v_pk_fma_f32 v[6:7], v[118:119], s[82:83], v[6:7] op_sel_hi:[0,1,1]
	v_readlane_b32 s86, v3, 29
	s_waitcnt vmcnt(35)
	v_fmac_f32_e32 v1, s24, v120
	v_readlane_b32 s87, v11, 29
	v_readlane_b32 s24, v13, 29
	v_pk_fma_f32 v[6:7], v[120:121], s[84:85], v[6:7] op_sel_hi:[0,1,1]
	v_readlane_b32 s88, v3, 30
	s_waitcnt vmcnt(34)
	v_fmac_f32_e32 v1, s24, v122
	v_readlane_b32 s89, v11, 30
	v_pk_fma_f32 v[6:7], v[122:123], s[86:87], v[6:7] op_sel_hi:[0,1,1]
	v_readlane_b32 s14, v13, 30
	s_waitcnt vmcnt(33)
	v_pk_fma_f32 v[6:7], v[124:125], s[88:89], v[6:7] op_sel_hi:[0,1,1]
	v_readlane_b32 s15, v11, 31
	v_fmac_f32_e32 v1, s14, v124
	v_readlane_b32 s14, v3, 31
	v_readlane_b32 s24, v13, 31
	v_readlane_b32 s26, v3, 32
	v_readlane_b32 s27, v11, 32
	s_waitcnt vmcnt(32)
	v_fmac_f32_e32 v1, s24, v68
	v_readlane_b32 s24, v13, 32
	v_pk_fma_f32 v[6:7], v[68:69], s[14:15], v[6:7] op_sel_hi:[0,1,1]
	v_readlane_b32 s28, v3, 33
	s_waitcnt vmcnt(31)
	v_fmac_f32_e32 v1, s24, v74
	v_readlane_b32 s29, v11, 33
	v_readlane_b32 s24, v13, 33
	v_pk_fma_f32 v[6:7], v[74:75], s[26:27], v[6:7] op_sel_hi:[0,1,1]
	v_readlane_b32 s52, v3, 34
	s_waitcnt vmcnt(30)
	v_fmac_f32_e32 v1, s24, v78
	v_readlane_b32 s53, v11, 34
	v_readlane_b32 s24, v13, 34
	v_pk_fma_f32 v[6:7], v[78:79], s[28:29], v[6:7] op_sel_hi:[0,1,1]
	v_readlane_b32 s54, v3, 35
	s_waitcnt vmcnt(29)
	v_fmac_f32_e32 v1, s24, v84
	v_readlane_b32 s55, v11, 35
	v_readlane_b32 s24, v13, 35
	v_pk_fma_f32 v[6:7], v[84:85], s[52:53], v[6:7] op_sel_hi:[0,1,1]
	v_readlane_b32 s78, v3, 36
	s_waitcnt vmcnt(28)
	v_fmac_f32_e32 v1, s24, v90
	v_readlane_b32 s79, v11, 36
	v_readlane_b32 s24, v13, 36
	v_pk_fma_f32 v[6:7], v[90:91], s[54:55], v[6:7] op_sel_hi:[0,1,1]
	v_readlane_b32 s80, v3, 37
	s_waitcnt vmcnt(27)
	v_fmac_f32_e32 v1, s24, v94
	v_readlane_b32 s81, v11, 37
	v_readlane_b32 s24, v13, 37
	v_pk_fma_f32 v[6:7], v[94:95], s[78:79], v[6:7] op_sel_hi:[0,1,1]
	v_readlane_b32 s82, v3, 38
	s_waitcnt vmcnt(26)
	v_fmac_f32_e32 v1, s24, v100
	v_readlane_b32 s83, v11, 38
	v_readlane_b32 s24, v13, 38
	v_pk_fma_f32 v[6:7], v[100:101], s[80:81], v[6:7] op_sel_hi:[0,1,1]
	v_readlane_b32 s84, v3, 39
	s_waitcnt vmcnt(25)
	v_fmac_f32_e32 v1, s24, v104
	v_readlane_b32 s85, v11, 39
	v_readlane_b32 s24, v13, 39
	v_pk_fma_f32 v[6:7], v[104:105], s[82:83], v[6:7] op_sel_hi:[0,1,1]
	v_readlane_b32 s86, v3, 40
	s_waitcnt vmcnt(24)
	v_fmac_f32_e32 v1, s24, v108
	v_readlane_b32 s87, v11, 40
	v_readlane_b32 s24, v13, 40
	v_pk_fma_f32 v[6:7], v[108:109], s[84:85], v[6:7] op_sel_hi:[0,1,1]
	v_readlane_b32 s88, v3, 41
	s_waitcnt vmcnt(23)
	v_fmac_f32_e32 v1, s24, v112
	v_readlane_b32 s89, v11, 41
	v_pk_fma_f32 v[6:7], v[112:113], s[86:87], v[6:7] op_sel_hi:[0,1,1]
	v_readlane_b32 s14, v13, 41
	s_waitcnt vmcnt(22)
	v_pk_fma_f32 v[6:7], v[114:115], s[88:89], v[6:7] op_sel_hi:[0,1,1]
	v_readlane_b32 s15, v11, 42
	v_fmac_f32_e32 v1, s14, v114
	v_readlane_b32 s14, v3, 42
	v_readlane_b32 s26, v3, 43
	v_readlane_b32 s27, v11, 43
	s_waitcnt vmcnt(21)
	v_pk_fma_f32 v[6:7], v[54:55], s[14:15], v[6:7] op_sel_hi:[0,1,1]
	v_readlane_b32 s24, v13, 42
	v_readlane_b32 s28, v3, 44
	v_readlane_b32 s29, v11, 44
	s_waitcnt vmcnt(20)
	v_pk_fma_f32 v[6:7], v[58:59], s[26:27], v[6:7] op_sel_hi:[0,1,1]
	v_fmac_f32_e32 v1, s24, v54
	v_readlane_b32 s24, v13, 43
	v_readlane_b32 s52, v3, 45
	v_readlane_b32 s53, v11, 45
	s_waitcnt vmcnt(19)
	v_pk_fma_f32 v[6:7], v[62:63], s[28:29], v[6:7] op_sel_hi:[0,1,1]
	v_fmac_f32_e32 v1, s24, v58
	v_readlane_b32 s24, v13, 44
	v_readlane_b32 s54, v3, 46
	v_readlane_b32 s55, v11, 46
	s_waitcnt vmcnt(18)
	v_pk_fma_f32 v[6:7], v[66:67], s[52:53], v[6:7] op_sel_hi:[0,1,1]
	v_fmac_f32_e32 v1, s24, v62
	v_readlane_b32 s24, v13, 45
	v_readlane_b32 s78, v3, 47
	v_readlane_b32 s79, v11, 47
	s_waitcnt vmcnt(17)
	v_pk_fma_f32 v[6:7], v[70:71], s[54:55], v[6:7] op_sel_hi:[0,1,1]
	v_fmac_f32_e32 v1, s24, v66
	v_readlane_b32 s24, v13, 46
	v_readlane_b32 s80, v3, 48
	v_readlane_b32 s81, v11, 48
	s_waitcnt vmcnt(16)
; __global__ void __launch_bounds__(NTHR, 2) fwd_kernel(Args args) {
;     ...
;                 for (int kk = 0; kk < 64; ++kk) {
;                     a0 += wv[kk] * __builtin_bit_cast(float, __builtin_amdgcn_readlane(__builtin_bit_cast(int, c0), kk));
;                     a1 += wv[kk] * __builtin_bit_cast(float, __builtin_amdgcn_readlane(__builtin_bit_cast(int, c1), kk));
;                     a2 += wv[kk] * __builtin_bit_cast(float, __builtin_amdgcn_readlane(__builtin_bit_cast(int, c2), kk));
;                 }
;             }
;             atomicAdd(MODA + col, __float2int_rn(a0 * 16777216.f)); atomicAdd(MODA + NMOD + col, __float2int_rn(a1 * 16777216.f)); atomicAdd(MODA + 2 * NMOD + col, __float2int_rn(a2 * 16777216.f));
;     ...
;             TR_RUN(-I_GV, I_IN + I_UP, gw < I_GV ? gw + NGW : gw, NGW);
	v_pk_fma_f32 v[6:7], v[76:77], s[78:79], v[6:7] op_sel_hi:[0,1,1]
	v_fmac_f32_e32 v1, s24, v70
	v_readlane_b32 s24, v13, 47
	v_readlane_b32 s82, v3, 49
	v_readlane_b32 s83, v11, 49
	s_waitcnt vmcnt(15)
	v_pk_fma_f32 v[6:7], v[80:81], s[80:81], v[6:7] op_sel_hi:[0,1,1]
	v_fmac_f32_e32 v1, s24, v76
	v_readlane_b32 s24, v13, 48
	v_readlane_b32 s84, v3, 50
	v_readlane_b32 s85, v11, 50
	s_waitcnt vmcnt(14)
	v_pk_fma_f32 v[6:7], v[86:87], s[82:83], v[6:7] op_sel_hi:[0,1,1]
	v_fmac_f32_e32 v1, s24, v80
	v_readlane_b32 s24, v13, 49
	v_readlane_b32 s86, v3, 51
	v_readlane_b32 s87, v11, 51
	s_waitcnt vmcnt(13)
	v_pk_fma_f32 v[6:7], v[92:93], s[84:85], v[6:7] op_sel_hi:[0,1,1]
	v_fmac_f32_e32 v1, s24, v86
	v_readlane_b32 s24, v13, 50
	v_readlane_b32 s88, v13, 51
	s_waitcnt vmcnt(12)
	v_pk_fma_f32 v[6:7], v[88:89], s[86:87], v[6:7] op_sel_hi:[0,1,1]
	v_readlane_b32 s89, v13, 52
	s_waitcnt vmcnt(11)
	v_mov_b32_e32 v89, v96
	v_fmac_f32_e32 v1, s24, v92
	v_pk_mul_f32 v[8:9], v[88:89], s[88:89]
	v_readlane_b32 s26, v13, 53
	v_add_f32_e32 v1, v1, v8
	v_readlane_b32 s27, v13, 54
	v_add_f32_e32 v1, v1, v9
	v_readlane_b32 s52, v13, 55
	s_waitcnt vmcnt(9)
	v_pk_mul_f32 v[8:9], v[44:45], s[26:27]
	v_readlane_b32 s53, v13, 56
	v_add_f32_e32 v1, v1, v8
	v_add_f32_e32 v1, v1, v9
	s_waitcnt vmcnt(7)
	v_pk_mul_f32 v[8:9], v[48:49], s[52:53]
	v_readlane_b32 s78, v13, 57
	v_add_f32_e32 v1, v1, v8
	v_readlane_b32 s79, v13, 58
	v_add_f32_e32 v1, v1, v9
	v_readlane_b32 s82, v13, 59
	s_waitcnt vmcnt(5)
	v_pk_mul_f32 v[8:9], v[50:51], s[78:79]
	v_readlane_b32 s83, v13, 60
	v_add_f32_e32 v1, v1, v8
	v_add_f32_e32 v1, v1, v9
	s_waitcnt vmcnt(3)
	v_pk_mul_f32 v[8:9], v[60:61], s[82:83]
	v_readlane_b32 s93, v11, 52
	v_add_f32_e32 v1, v1, v8
	v_readlane_b32 s86, v13, 61
	v_readlane_b32 s87, v13, 62
	v_pk_fma_f32 v[6:7], v[96:97], s[92:93], v[6:7] op_sel_hi:[0,1,1]
	v_readlane_b32 s14, v3, 53
	v_readlane_b32 s15, v11, 53
	v_add_f32_e32 v1, v1, v9
	s_waitcnt vmcnt(0)
	v_pk_mul_f32 v[8:9], v[72:73], s[86:87]
	v_readlane_b32 s28, v3, 54
	v_readlane_b32 s29, v11, 54
	v_add_f32_e32 v1, v1, v8
	v_pk_fma_f32 v[6:7], v[44:45], s[14:15], v[6:7] op_sel_hi:[0,1,1]
	v_mov_b32_e32 v8, v45
	v_readlane_b32 s26, v3, 55
	v_readlane_b32 s27, v11, 55
	v_pk_fma_f32 v[6:7], v[8:9], s[28:29], v[6:7] op_sel_hi:[0,1,1]
	v_readlane_b32 s54, v3, 56
	v_readlane_b32 s55, v11, 56
	v_pk_fma_f32 v[6:7], v[48:49], s[26:27], v[6:7] op_sel_hi:[0,1,1]
	v_mov_b32_e32 v8, v49
	v_readlane_b32 s52, v3, 57
	v_readlane_b32 s53, v11, 57
	v_pk_fma_f32 v[6:7], v[8:9], s[54:55], v[6:7] op_sel_hi:[0,1,1]
	v_readlane_b32 s80, v3, 58
	v_readlane_b32 s81, v11, 58
	v_pk_fma_f32 v[6:7], v[50:51], s[52:53], v[6:7] op_sel_hi:[0,1,1]
	v_mov_b32_e32 v8, v51
	v_readlane_b32 s78, v3, 59
	v_readlane_b32 s79, v11, 59
	v_pk_fma_f32 v[6:7], v[8:9], s[80:81], v[6:7] op_sel_hi:[0,1,1]
	v_readlane_b32 s84, v3, 60
	v_readlane_b32 s85, v11, 60
	v_pk_fma_f32 v[6:7], v[60:61], s[78:79], v[6:7] op_sel_hi:[0,1,1]
	v_mov_b32_e32 v8, v61
	v_readlane_b32 s82, v3, 61
	v_readlane_b32 s83, v11, 61
	v_pk_fma_f32 v[6:7], v[8:9], s[84:85], v[6:7] op_sel_hi:[0,1,1]
	v_readlane_b32 s88, v3, 62
	v_readlane_b32 s89, v11, 62
	v_pk_fma_f32 v[6:7], v[72:73], s[82:83], v[6:7] op_sel_hi:[0,1,1]
	v_mov_b32_e32 v8, v73
	v_add_f32_e32 v1, v1, v9
	v_readlane_b32 s86, v3, 63
	v_readlane_b32 s87, v11, 63
	v_pk_fma_f32 v[6:7], v[8:9], s[88:89], v[6:7] op_sel_hi:[0,1,1]
	v_readlane_b32 s14, v13, 63
	v_pk_fma_f32 v[6:7], v[82:83], s[86:87], v[6:7] op_sel_hi:[0,1,1]
	s_nop 0
	v_fmac_f32_e32 v1, s14, v82
	s_cbranch_scc0 .LBB0_8
	s_mulk_i32 s12, 0xc0
	v_mul_f32_e32 v4, 0x4b800000, v6
	s_sub_i32 s4, s20, s12
	v_rndne_f32_e32 v4, v4
	v_lshl_or_b32 v2, s4, 6, v216
	v_cvt_i32_f32_e32 v6, v4
	v_ashrrev_i32_e32 v3, 31, v2
	v_lshlrev_b64 v[2:3], 2, v[2:3]
	v_lshl_add_u64 v[4:5], s[10:11], 0, v[2:3]
	global_atomic_add v[4:5], v6, off
	v_mul_f32_e32 v4, 0x4b800000, v7
	v_rndne_f32_e32 v4, v4
	v_mul_f32_e32 v1, 0x4b800000, v1
	v_lshl_add_u64 v[2:3], s[18:19], 0, v[2:3]
	v_cvt_i32_f32_e32 v6, v4
	v_rndne_f32_e32 v1, v1
	v_add_co_u32_e32 v4, vcc, 0x1c000, v2
	v_cvt_i32_f32_e32 v1, v1
	s_nop 0
	v_addc_co_u32_e32 v5, vcc, 0, v3, vcc
	v_add_co_u32_e32 v2, vcc, 0x28000, v2
	global_atomic_add v[4:5], v6, off
	s_nop 0
	v_addc_co_u32_e32 v3, vcc, 0, v3, vcc
	global_atomic_add v[2:3], v1, off
	v_readlane_b32 s84, v255, 2
	v_readlane_b32 s54, v255, 6
	v_readlane_b32 s82, v255, 4
	s_movk_i32 s6, 0x600
	v_readlane_b32 s85, v255, 3
	s_mov_b32 s88, s25
	v_readlane_b32 s55, v255, 7
	v_readlane_b32 s83, v255, 5

; #define LAS __attribute__((address_space(3)))
; #define LDS_WAIT() asm volatile("s_waitcnt lgkmcnt(0)" ::: "memory")
; __device__ __forceinline__ void tr_load(const float* W, int N, int k0, int n0, f32x4 (&v)[16], int lane) {
;     ...
;     for (int i = 0; i < 16; ++i) v[i] = __builtin_nontemporal_load((const f32x4*)(W + (size_t)(k0 + 4 * i + (lane >> 4)) * N + n0 + 4 * (lane & 15)));
; }
; __device__ __forceinline__ void tr_to_lds(const f32x4 (&v)[16], LAS float* scr, int lane) {
; #pragma unroll
;     for (int i = 0; i < 16; ++i) { LAS float* d = scr + (4 * i + (lane >> 4)) * 65 + 4 * (lane & 15); d[0] = v[i].x; d[1] = v[i].y; d[2] = v[i].z; d[3] = v[i].w; }
;     LDS_WAIT(); asm volatile("" ::: "memory");
.LBB0_15:
	v_add_u32_e32 v67, 0x410, v95
	s_waitcnt vmcnt(15)
	ds_write2_b32 v95, v2, v3 offset1:1
	ds_write2_b32 v95, v4, v5 offset0:2 offset1:3
	s_waitcnt vmcnt(14)
	ds_write2_b32 v67, v6, v7 offset1:1
	v_add_u32_e32 v67, 0x418, v95
	ds_write2_b32 v67, v8, v9 offset1:1
	v_add_u32_e32 v67, 0x820, v95
	s_waitcnt vmcnt(13)
	ds_write2_b32 v67, v10, v11 offset1:1
	v_add_u32_e32 v67, 0x828, v95
	ds_write2_b32 v67, v12, v13 offset1:1
	v_add_u32_e32 v67, 0xc30, v95
	s_waitcnt vmcnt(12)
	ds_write2_b32 v67, v14, v15 offset1:1
	v_add_u32_e32 v67, 0xc38, v95
	ds_write2_b32 v67, v16, v17 offset1:1
	v_add_u32_e32 v67, 0x1040, v95
	s_waitcnt vmcnt(11)
	ds_write2_b32 v67, v18, v19 offset1:1
	v_add_u32_e32 v67, 0x1048, v95
	ds_write2_b32 v67, v20, v21 offset1:1
	v_add_u32_e32 v67, 0x1450, v95
	s_waitcnt vmcnt(10)
	ds_write2_b32 v67, v22, v23 offset1:1
	v_add_u32_e32 v67, 0x1458, v95
	ds_write2_b32 v67, v24, v25 offset1:1
	v_add_u32_e32 v67, 0x1860, v95
	s_waitcnt vmcnt(9)
	ds_write2_b32 v67, v26, v27 offset1:1
	v_add_u32_e32 v67, 0x1868, v95
	ds_write2_b32 v67, v28, v29 offset1:1
	v_add_u32_e32 v67, 0x1c70, v95
	s_waitcnt vmcnt(8)
	ds_write2_b32 v67, v30, v31 offset1:1
	v_add_u32_e32 v67, 0x1c78, v95
	ds_write2_b32 v67, v32, v33 offset1:1
	v_add_u32_e32 v67, 0x2080, v95
	s_waitcnt vmcnt(7)
	ds_write2_b32 v67, v34, v35 offset1:1
	v_add_u32_e32 v67, 0x2088, v95
	ds_write2_b32 v67, v36, v37 offset1:1
	v_add_u32_e32 v67, 0x2490, v95
	s_waitcnt vmcnt(6)
	ds_write2_b32 v67, v38, v39 offset1:1
	v_add_u32_e32 v67, 0x2498, v95
	ds_write2_b32 v67, v40, v41 offset1:1
	v_add_u32_e32 v67, 0x28a0, v95
	s_waitcnt vmcnt(5)
	ds_write2_b32 v67, v42, v43 offset1:1
	v_add_u32_e32 v67, 0x28a8, v95
	ds_write2_b32 v67, v44, v45 offset1:1
	v_add_u32_e32 v67, 0x2cb0, v95
	s_waitcnt vmcnt(4)
	ds_write2_b32 v67, v46, v47 offset1:1
	v_add_u32_e32 v67, 0x2cb8, v95
	ds_write2_b32 v67, v48, v49 offset1:1
	v_add_u32_e32 v67, 0x30c0, v95
	s_waitcnt vmcnt(3)
	ds_write2_b32 v67, v50, v51 offset1:1
	v_add_u32_e32 v67, 0x30c8, v95
	ds_write2_b32 v67, v52, v53 offset1:1
	v_add_u32_e32 v67, 0x34d0, v95
	s_waitcnt vmcnt(2)
	ds_write2_b32 v67, v54, v55 offset1:1
	v_add_u32_e32 v67, 0x34d8, v95
	ds_write2_b32 v67, v56, v57 offset1:1
	v_add_u32_e32 v67, 0x38e0, v95
	s_waitcnt vmcnt(1)
	ds_write2_b32 v67, v58, v59 offset1:1
	v_add_u32_e32 v67, 0x38e8, v95
	ds_write2_b32 v67, v60, v61 offset1:1
	v_add_u32_e32 v67, 0x3cf0, v95
	s_waitcnt vmcnt(0)
	ds_write2_b32 v67, v62, v63 offset1:1
	v_add_u32_e32 v67, 0x3cf8, v95
	ds_write2_b32 v67, v64, v65 offset1:1
	s_movk_i32 s37, 0x600
	s_cmpk_gt_i32 s20, 0x5ff
	s_cselect_b32 s37, 0x200, s37
	s_add_i32 s37, s37, s4
	s_waitcnt lgkmcnt(0)
	s_add_i32 s5, s37, 0xfffffa00
	s_movk_i32 s6, 0x17ff
	s_cmpk_gt_i32 s20, 0x5ff
	s_cselect_b32 s6, 0x23ff, s6
	s_cmp_gt_i32 s5, s6
	s_cselect_b64 s[8:9], -1, 0
	s_and_b64 vcc, exec, s[8:9]
	s_cbranch_vccnz .LBB0_17
	s_add_i32 s6, s37, 0xffffec00
	s_cmpk_lt_i32 s5, 0xe00
	s_cselect_b32 s5, s5, s6
	s_cselect_b32 s6, 56, 0x68
	s_cselect_b32 s24, s3, 0x2c00
	s_add_u32 s6, s0, s6
	s_addc_u32 s7, s1, 0
	s_lshr_b32 s12, s24, 6
	s_abs_i32 s13, s12
	v_cvt_f32_u32_e32 v2, s13
	s_sub_i32 s31, 0, s13
	s_abs_i32 s25, s5
	s_xor_b32 s30, s5, s12
	v_rcp_iflag_f32_e32 v2, v2
	s_ashr_i32 s30, s30, 31
	s_load_dwordx2 s[6:7], s[6:7], 0x0
	v_mov_b32_e32 v67, v69
	v_mul_f32_e32 v2, 0x4f7ffffe, v2
	v_cvt_u32_f32_e32 v2, v2
	s_nop 0
	v_readfirstlane_b32 s34, v2
	s_mul_i32 s31, s31, s34
	s_mul_hi_u32 s31, s34, s31
	s_add_i32 s34, s34, s31
	s_mul_hi_u32 s31, s25, s34
	s_mul_i32 s34, s31, s13
	s_sub_i32 s25, s25, s34
	s_add_i32 s35, s31, 1
	s_sub_i32 s34, s25, s13
	s_cmp_ge_u32 s25, s13
	s_cselect_b32 s31, s35, s31
	s_cselect_b32 s25, s34, s25
	s_add_i32 s34, s31, 1
	s_cmp_ge_u32 s25, s13
	s_cselect_b32 s13, s34, s31
	s_xor_b32 s13, s13, s30
	s_sub_i32 s13, s13, s30
	s_mul_i32 s12, s13, s12
	s_sub_i32 s5, s5, s12
	s_lshl_b32 s12, s5, 6
	v_lshl_or_b32 v64, s13, 6, v1
	s_ashr_i32 s13, s12, 31
	s_lshl_b64 s[12:13], s[12:13], 2
	s_waitcnt lgkmcnt(0)
	s_add_u32 s6, s6, s12
	s_addc_u32 s7, s7, s13
	v_or_b32_e32 v10, 8, v64
	v_lshl_add_u64 v[58:59], s[6:7], 0, v[66:67]
	v_or_b32_e32 v4, 4, v64
	v_mad_i64_i32 v[10:11], s[6:7], v10, s24, 0
	v_mad_i64_i32 v[2:3], s[6:7], v64, s24, 0
	v_mad_i64_i32 v[4:5], s[6:7], v4, s24, 0
	v_lshl_add_u64 v[18:19], v[10:11], 2, v[58:59]
	v_or_b32_e32 v10, 12, v64
	v_lshl_add_u64 v[2:3], v[2:3], 2, v[58:59]
	v_lshl_add_u64 v[6:7], v[4:5], 2, v[58:59]
	v_mad_i64_i32 v[10:11], s[6:7], v10, s24, 0
	global_load_dwordx4 v[2:5], v[2:3], off nt
	s_nop 0
	global_load_dwordx4 v[6:9], v[6:7], off nt
	v_lshl_add_u64 v[20:21], v[10:11], 2, v[58:59]
	global_load_dwordx4 v[10:13], v[18:19], off nt
	global_load_dwordx4 v[14:17], v[20:21], off nt
	v_or_b32_e32 v18, 16, v64
	v_mad_i64_i32 v[18:19], s[6:7], v18, s24, 0
	v_lshl_add_u64 v[26:27], v[18:19], 2, v[58:59]
	v_or_b32_e32 v18, 20, v64
	v_mad_i64_i32 v[18:19], s[6:7], v18, s24, 0
	v_lshl_add_u64 v[28:29], v[18:19], 2, v[58:59]
	global_load_dwordx4 v[18:21], v[26:27], off nt
	global_load_dwordx4 v[22:25], v[28:29], off nt
	v_or_b32_e32 v26, 24, v64
	v_mad_i64_i32 v[26:27], s[6:7], v26, s24, 0
	v_lshl_add_u64 v[34:35], v[26:27], 2, v[58:59]
	v_or_b32_e32 v26, 28, v64
	v_mad_i64_i32 v[26:27], s[6:7], v26, s24, 0
	v_lshl_add_u64 v[36:37], v[26:27], 2, v[58:59]
	global_load_dwordx4 v[26:29], v[34:35], off nt
	global_load_dwordx4 v[30:33], v[36:37], off nt
	v_or_b32_e32 v34, 32, v64
	v_mad_i64_i32 v[34:35], s[6:7], v34, s24, 0
	v_lshl_add_u64 v[42:43], v[34:35], 2, v[58:59]
	v_or_b32_e32 v34, 36, v64
	v_mad_i64_i32 v[34:35], s[6:7], v34, s24, 0
	v_lshl_add_u64 v[44:45], v[34:35], 2, v[58:59]
	global_load_dwordx4 v[34:37], v[42:43], off nt
	global_load_dwordx4 v[38:41], v[44:45], off nt
	v_or_b32_e32 v42, 40, v64
	v_mad_i64_i32 v[42:43], s[6:7], v42, s24, 0
	v_lshl_add_u64 v[50:51], v[42:43], 2, v[58:59]
	v_or_b32_e32 v42, 44, v64
	v_mad_i64_i32 v[42:43], s[6:7], v42, s24, 0
	v_lshl_add_u64 v[52:53], v[42:43], 2, v[58:59]
	global_load_dwordx4 v[42:45], v[50:51], off nt
	global_load_dwordx4 v[46:49], v[52:53], off nt
	v_or_b32_e32 v50, 48, v64
	v_mad_i64_i32 v[50:51], s[6:7], v50, s24, 0
	v_lshl_add_u64 v[60:61], v[50:51], 2, v[58:59]
	v_or_b32_e32 v50, 52, v64
	v_mad_i64_i32 v[50:51], s[6:7], v50, s24, 0
	v_lshl_add_u64 v[62:63], v[50:51], 2, v[58:59]
	global_load_dwordx4 v[50:53], v[60:61], off nt
	global_load_dwordx4 v[54:57], v[62:63], off nt
	v_or_b32_e32 v60, 56, v64
	v_mad_i64_i32 v[60:61], s[6:7], v60, s24, 0
	v_lshl_add_u64 v[72:73], v[60:61], 2, v[58:59]
	v_or_b32_e32 v60, 60, v64
	v_mad_i64_i32 v[60:61], s[6:7], v60, s24, 0
	v_lshl_add_u64 v[74:75], v[60:61], 2, v[58:59]
	global_load_dwordx4 v[58:61], v[72:73], off nt
	global_load_dwordx4 v[62:65], v[74:75], off nt
